# combination: layer-1 late modulation columns in GLU idle workgroups (pipelined GEMV), conversion loop with 3 items in flight, norm rows with all g/scale/shift loads issued together and next-row x pref
# speedup vs baseline: 1.0187x; 1.0090x over previous
.LBB0_192:
	s_lshl_b32 s44, s0, 8
	v_add_u32_e32 v186, s44, v5
	s_addk_i32 s44, 0xf000
	s_ashr_i32 s44, s44, 10
	s_add_i32 s44, s44, 1
	s_cmp_lt_i32 s0, 16
	v_lshl_or_b32 v184, s82, 8, v153
	s_cselect_b32 s0, 0, s44
	v_ashrrev_i32_e32 v187, 31, v186
	v_ashrrev_i32_e32 v185, 31, v184
	s_mul_hi_i32 s45, s0, 0xc000
	s_mul_i32 s0, s0, 0xc000
	v_lshlrev_b64 v[156:157], 11, v[186:187]
	s_cselect_b32 s73, s11, s13
	s_cselect_b32 s72, s10, s12
	s_add_u32 s44, s42, s0
	v_lshl_add_u64 v[156:157], v[156:157], 0, v[184:185]
	s_addc_u32 s45, s64, s45
	v_lshlrev_b64 v[182:183], 2, v[156:157]
	v_lshl_add_u64 v[134:135], v[184:185], 2, s[44:45]
	v_lshl_add_u64 v[160:161], s[72:73], 0, v[182:183]
	global_load_dwordx4 v[138:141], v[134:135], off offset:16
	global_load_dwordx4 v[146:149], v[134:135], off
	global_load_dwordx4 v[130:133], v[134:135], off offset:528
	s_nop 0
	global_load_dwordx4 v[134:137], v[134:135], off offset:512
	s_and_b64 vcc, exec, s[6:7]
	v_lshl_add_u64 v[156:157], s[60:61], 0, v[182:183]
	global_load_dwordx4 v[190:193], v[160:161], off
	global_load_dwordx4 v[194:197], v[160:161], off offset:16
	global_load_dwordx4 v[198:201], v[160:161], off offset:512
	global_load_dwordx4 v[202:205], v[160:161], off offset:528
	s_mov_b64 s[44:45], 0x20000
	v_lshl_add_u64 v[160:161], v[160:161], 0, s[44:45]
	global_load_dwordx4 v[206:209], v[160:161], off
	global_load_dwordx4 v[210:213], v[160:161], off offset:16
	global_load_dwordx4 v[214:217], v[160:161], off offset:512
	global_load_dwordx4 v[218:221], v[160:161], off offset:528
	s_mov_b64 s[44:45], 0x20000
	v_lshl_add_u64 v[160:161], v[160:161], 0, s[44:45]
	s_waitcnt vmcnt(0)
	v_pk_fma_f32 v[144:145], v[144:145], v[148:149], v[192:193]
	v_pk_fma_f32 v[142:143], v[142:143], v[146:147], v[190:191]
	v_pk_fma_f32 v[128:129], v[128:129], v[140:141], v[196:197]
	v_pk_fma_f32 v[126:127], v[126:127], v[138:139], v[194:195]
	v_pk_fma_f32 v[124:125], v[124:125], v[136:137], v[200:201]
	v_pk_fma_f32 v[122:123], v[122:123], v[134:135], v[198:199]
	v_pk_fma_f32 v[120:121], v[120:121], v[132:133], v[204:205]
	v_pk_fma_f32 v[118:119], v[118:119], v[130:131], v[202:203]
	global_store_dwordx4 v[156:157], v[142:145], off
	global_store_dwordx4 v[156:157], v[126:129], off offset:16
	global_store_dwordx4 v[156:157], v[122:125], off offset:512
	global_store_dwordx4 v[156:157], v[118:121], off offset:528
	s_mov_b64 s[44:45], 0x20000
	v_lshl_add_u64 v[156:157], v[156:157], 0, s[44:45]
	v_pk_fma_f32 v[116:117], v[116:117], v[148:149], v[208:209]
	v_pk_fma_f32 v[114:115], v[114:115], v[146:147], v[206:207]
	v_pk_fma_f32 v[112:113], v[112:113], v[140:141], v[212:213]
	v_pk_fma_f32 v[110:111], v[110:111], v[138:139], v[210:211]
	v_pk_fma_f32 v[108:109], v[108:109], v[136:137], v[216:217]
	v_pk_fma_f32 v[106:107], v[106:107], v[134:135], v[214:215]
	v_pk_fma_f32 v[104:105], v[104:105], v[132:133], v[220:221]
	v_pk_fma_f32 v[102:103], v[102:103], v[130:131], v[218:219]
	global_store_dwordx4 v[156:157], v[114:117], off
	global_store_dwordx4 v[156:157], v[110:113], off offset:16
	global_store_dwordx4 v[156:157], v[106:109], off offset:512
	global_store_dwordx4 v[156:157], v[102:105], off offset:528
	s_mov_b64 s[44:45], 0x20000
	v_lshl_add_u64 v[156:157], v[156:157], 0, s[44:45]
	global_load_dwordx4 v[190:193], v[160:161], off
	global_load_dwordx4 v[194:197], v[160:161], off offset:16
	global_load_dwordx4 v[198:201], v[160:161], off offset:512
	global_load_dwordx4 v[202:205], v[160:161], off offset:528
	s_mov_b64 s[44:45], 0x20000
	v_lshl_add_u64 v[160:161], v[160:161], 0, s[44:45]
	global_load_dwordx4 v[206:209], v[160:161], off
	global_load_dwordx4 v[210:213], v[160:161], off offset:16
	global_load_dwordx4 v[214:217], v[160:161], off offset:512
	global_load_dwordx4 v[218:221], v[160:161], off offset:528
	s_mov_b64 s[44:45], 0xa0000
	v_lshl_add_u64 v[160:161], v[160:161], 0, s[44:45]
	global_load_dwordx4 v[142:145], v[160:161], off
	global_load_dwordx4 v[126:129], v[160:161], off offset:16
	global_load_dwordx4 v[122:125], v[160:161], off offset:512
	global_load_dwordx4 v[118:121], v[160:161], off offset:528
	s_mov_b64 s[44:45], 0x20000
	v_lshl_add_u64 v[160:161], v[160:161], 0, s[44:45]
	global_load_dwordx4 v[114:117], v[160:161], off
	global_load_dwordx4 v[110:113], v[160:161], off offset:16
	global_load_dwordx4 v[106:109], v[160:161], off offset:512
	global_load_dwordx4 v[102:105], v[160:161], off offset:528
	s_mov_b64 s[44:45], 0x20000
	v_lshl_add_u64 v[160:161], v[160:161], 0, s[44:45]
	s_waitcnt vmcnt(8)
	v_pk_fma_f32 v[100:101], v[100:101], v[148:149], v[192:193]
	v_pk_fma_f32 v[98:99], v[98:99], v[146:147], v[190:191]
	v_pk_fma_f32 v[96:97], v[96:97], v[140:141], v[196:197]
	v_pk_fma_f32 v[94:95], v[94:95], v[138:139], v[194:195]
	v_pk_fma_f32 v[92:93], v[92:93], v[136:137], v[200:201]
	v_pk_fma_f32 v[90:91], v[90:91], v[134:135], v[198:199]
	v_pk_fma_f32 v[88:89], v[88:89], v[132:133], v[204:205]
	v_pk_fma_f32 v[86:87], v[86:87], v[130:131], v[202:203]
	global_store_dwordx4 v[156:157], v[98:101], off
	global_store_dwordx4 v[156:157], v[94:97], off offset:16
	global_store_dwordx4 v[156:157], v[90:93], off offset:512
	global_store_dwordx4 v[156:157], v[86:89], off offset:528
	s_mov_b64 s[44:45], 0x20000
	v_lshl_add_u64 v[156:157], v[156:157], 0, s[44:45]
	v_pk_fma_f32 v[84:85], v[84:85], v[148:149], v[208:209]
	v_pk_fma_f32 v[82:83], v[82:83], v[146:147], v[206:207]
	v_pk_fma_f32 v[80:81], v[80:81], v[140:141], v[212:213]
	v_pk_fma_f32 v[78:79], v[78:79], v[138:139], v[210:211]
	v_pk_fma_f32 v[76:77], v[76:77], v[136:137], v[216:217]
	v_pk_fma_f32 v[74:75], v[74:75], v[134:135], v[214:215]
	v_pk_fma_f32 v[72:73], v[72:73], v[132:133], v[220:221]
	v_pk_fma_f32 v[70:71], v[70:71], v[130:131], v[218:219]
	global_store_dwordx4 v[156:157], v[82:85], off
	global_store_dwordx4 v[156:157], v[78:81], off offset:16
	global_store_dwordx4 v[156:157], v[74:77], off offset:512
	global_store_dwordx4 v[156:157], v[70:73], off offset:528
	s_mov_b64 s[44:45], 0xa0000
	v_lshl_add_u64 v[156:157], v[156:157], 0, s[44:45]
	global_load_dwordx4 v[190:193], v[160:161], off
	global_load_dwordx4 v[194:197], v[160:161], off offset:16
	global_load_dwordx4 v[198:201], v[160:161], off offset:512
	global_load_dwordx4 v[202:205], v[160:161], off offset:528
	s_mov_b64 s[44:45], 0x20000
	v_lshl_add_u64 v[160:161], v[160:161], 0, s[44:45]
	global_load_dwordx4 v[206:209], v[160:161], off
	global_load_dwordx4 v[210:213], v[160:161], off offset:16
	global_load_dwordx4 v[214:217], v[160:161], off offset:512
	global_load_dwordx4 v[218:221], v[160:161], off offset:528
	s_waitcnt vmcnt(8)
	v_pk_fma_f32 v[68:69], v[68:69], v[148:149], v[144:145]
	v_pk_fma_f32 v[66:67], v[66:67], v[146:147], v[142:143]
	v_pk_fma_f32 v[64:65], v[64:65], v[140:141], v[128:129]
	v_pk_fma_f32 v[62:63], v[62:63], v[138:139], v[126:127]
	v_pk_fma_f32 v[60:61], v[60:61], v[136:137], v[124:125]
	v_pk_fma_f32 v[58:59], v[58:59], v[134:135], v[122:123]
	v_pk_fma_f32 v[56:57], v[56:57], v[132:133], v[120:121]
	v_pk_fma_f32 v[54:55], v[54:55], v[130:131], v[118:119]
	global_store_dwordx4 v[156:157], v[66:69], off
	global_store_dwordx4 v[156:157], v[62:65], off offset:16
	global_store_dwordx4 v[156:157], v[58:61], off offset:512
	global_store_dwordx4 v[156:157], v[54:57], off offset:528
	s_mov_b64 s[44:45], 0x20000
	v_lshl_add_u64 v[156:157], v[156:157], 0, s[44:45]
	v_pk_fma_f32 v[52:53], v[52:53], v[148:149], v[116:117]
	v_pk_fma_f32 v[50:51], v[50:51], v[146:147], v[114:115]
	v_pk_fma_f32 v[48:49], v[48:49], v[140:141], v[112:113]
	v_pk_fma_f32 v[46:47], v[46:47], v[138:139], v[110:111]
	v_pk_fma_f32 v[44:45], v[44:45], v[136:137], v[108:109]
	v_pk_fma_f32 v[42:43], v[42:43], v[134:135], v[106:107]
	v_pk_fma_f32 v[40:41], v[40:41], v[132:133], v[104:105]
	v_pk_fma_f32 v[38:39], v[38:39], v[130:131], v[102:103]
	global_store_dwordx4 v[156:157], v[50:53], off
	global_store_dwordx4 v[156:157], v[46:49], off offset:16
	global_store_dwordx4 v[156:157], v[42:45], off offset:512
	global_store_dwordx4 v[156:157], v[38:41], off offset:528
	s_mov_b64 s[44:45], 0x20000
	v_lshl_add_u64 v[156:157], v[156:157], 0, s[44:45]
	s_waitcnt vmcnt(0)
	v_pk_fma_f32 v[36:37], v[36:37], v[148:149], v[192:193]
	v_pk_fma_f32 v[34:35], v[34:35], v[146:147], v[190:191]
	v_pk_fma_f32 v[32:33], v[32:33], v[140:141], v[196:197]
	v_pk_fma_f32 v[30:31], v[30:31], v[138:139], v[194:195]
	v_pk_fma_f32 v[28:29], v[28:29], v[136:137], v[200:201]
	v_pk_fma_f32 v[26:27], v[26:27], v[134:135], v[198:199]
	v_pk_fma_f32 v[24:25], v[24:25], v[132:133], v[204:205]
	v_pk_fma_f32 v[22:23], v[22:23], v[130:131], v[202:203]
	global_store_dwordx4 v[156:157], v[34:37], off
	global_store_dwordx4 v[156:157], v[30:33], off offset:16
	global_store_dwordx4 v[156:157], v[26:29], off offset:512
	global_store_dwordx4 v[156:157], v[22:25], off offset:528
	s_mov_b64 s[44:45], 0x20000
	v_lshl_add_u64 v[156:157], v[156:157], 0, s[44:45]
	v_pk_fma_f32 v[20:21], v[20:21], v[148:149], v[208:209]
	v_pk_fma_f32 v[18:19], v[18:19], v[146:147], v[206:207]
	v_pk_fma_f32 v[12:13], v[12:13], v[140:141], v[212:213]
	v_pk_fma_f32 v[10:11], v[10:11], v[138:139], v[210:211]
	v_pk_fma_f32 v[8:9], v[8:9], v[136:137], v[216:217]
	v_pk_fma_f32 v[6:7], v[6:7], v[134:135], v[214:215]
	v_pk_fma_f32 v[2:3], v[2:3], v[132:133], v[220:221]
	v_pk_fma_f32 v[0:1], v[0:1], v[130:131], v[218:219]
	global_store_dwordx4 v[156:157], v[18:21], off
	global_store_dwordx4 v[156:157], v[10:13], off offset:16
	global_store_dwordx4 v[156:157], v[6:9], off offset:512
	global_store_dwordx4 v[156:157], v[0:3], off offset:528
	s_mov_b64 s[72:73], -1
	s_cbranch_vccnz .LBB0_181
	s_andn2_b64 vcc, exec, s[66:67]
	s_cbranch_vccnz .LBB0_180
	s_barrier
	s_branch .LBB0_180

.LBB0_448:
	s_add_i32 s3, s4, 0xfffff000
	s_lshr_b32 s3, s3, 10
	s_add_i32 s3, s3, 1
	s_and_b64 s[18:19], s[64:65], exec
	s_cselect_b32 s3, 0, s3
	s_mul_hi_u32 s5, s3, 0xc000
	s_mul_i32 s3, s3, 0xc000
	s_add_u32 s3, s93, s3
	s_addc_u32 s5, s34, s5
	s_add_u32 s66, s3, s0
	s_addc_u32 s67, s5, 0
	s_add_u32 s64, s3, s1
	s_addc_u32 s65, s5, 0
	s_add_u32 s18, s66, 0x1000
	s_addc_u32 s19, s67, 0
	s_add_u32 s36, s64, 0x1000
	s_addc_u32 s37, s65, 0
	global_load_dwordx4 v[92:95], v[40:41], off
	global_load_dwordx4 v[170:173], v54, s[66:67]
	global_load_dwordx4 v[202:205], v54, s[64:65]
	global_load_dwordx4 v[96:99], v[40:41], off offset:1024
	global_load_dwordx4 v[174:177], v54, s[66:67] offset:1024
	global_load_dwordx4 v[206:209], v54, s[64:65] offset:1024
	global_load_dwordx4 v[100:103], v[40:41], off offset:2048
	global_load_dwordx4 v[178:181], v54, s[66:67] offset:2048
	global_load_dwordx4 v[210:213], v54, s[64:65] offset:2048
	global_load_dwordx4 v[104:107], v[40:41], off offset:3072
	global_load_dwordx4 v[182:185], v54, s[66:67] offset:3072
	global_load_dwordx4 v[214:217], v54, s[64:65] offset:3072
	global_load_dwordx4 v[108:111], v[42:43], off
	global_load_dwordx4 v[186:189], v54, s[18:19]
	global_load_dwordx4 v[218:221], v54, s[36:37]
	global_load_dwordx4 v[112:115], v[44:45], off
	global_load_dwordx4 v[190:193], v54, s[18:19] offset:1024
	global_load_dwordx4 v[222:225], v54, s[36:37] offset:1024
	global_load_dwordx4 v[116:119], v[46:47], off
	global_load_dwordx4 v[194:197], v54, s[18:19] offset:2048
	global_load_dwordx4 v[226:229], v54, s[36:37] offset:2048
	global_load_dwordx4 v[120:123], v[48:49], off
	global_load_dwordx4 v[198:201], v54, s[18:19] offset:3072
	global_load_dwordx4 v[230:233], v54, s[36:37] offset:3072
	ds_bpermute_b32 v56, v5, v55
	v_lshl_add_u64 v[58:59], s[56:57], 0, v[50:51]
	s_mov_b32 s3, 0x12800000
	v_add_co_u32_e32 v58, vcc, s3, v58
	s_waitcnt lgkmcnt(0)
	v_add_f32_e32 v55, v55, v56
	ds_bpermute_b32 v56, v60, v55
	v_addc_co_u32_e32 v59, vcc, 0, v59, vcc
	s_add_i32 s4, s4, s10
	v_lshl_add_u64 v[50:51], v[50:51], 0, s[12:13]
	s_waitcnt lgkmcnt(0)
	v_add_f32_e32 v55, v55, v56
	ds_bpermute_b32 v56, v61, v55
	s_cmpk_gt_i32 s4, 0x2fff
	v_lshl_add_u64 v[52:53], v[52:53], 0, s[62:63]
	s_waitcnt lgkmcnt(0)
	v_add_f32_e32 v55, v55, v56
	ds_bpermute_b32 v56, v62, v55
	s_waitcnt lgkmcnt(0)
	v_add_f32_e32 v55, v55, v56
	ds_bpermute_b32 v56, v63, v55
	s_waitcnt lgkmcnt(0)
	v_add_f32_e32 v55, v55, v56
	ds_bpermute_b32 v56, v64, v55
	s_waitcnt lgkmcnt(0)
	v_add_f32_e32 v55, v55, v56
	v_fmamk_f32 v55, v55, 0x3a000000, v236
	v_rsq_f32_e32 v56, v55
	v_mov_b32_e32 v55, v4
	s_nop 0
	v_pk_mul_f32 v[6:7], v[6:7], v[56:57] op_sel_hi:[1,0]
	v_pk_mul_f32 v[8:9], v[8:9], v[56:57] op_sel_hi:[1,0]
	v_pk_mul_f32 v[0:1], v[0:1], v[56:57] op_sel_hi:[1,0]
	v_pk_mul_f32 v[2:3], v[2:3], v[56:57] op_sel_hi:[1,0]
	v_pk_mul_f32 v[22:23], v[22:23], v[56:57] op_sel_hi:[1,0]
	v_pk_mul_f32 v[24:25], v[24:25], v[56:57] op_sel_hi:[1,0]
	v_pk_mul_f32 v[18:19], v[18:19], v[56:57] op_sel_hi:[1,0]
	v_pk_mul_f32 v[20:21], v[20:21], v[56:57] op_sel_hi:[1,0]
	v_pk_mul_f32 v[10:11], v[10:11], v[56:57] op_sel_hi:[1,0]
	v_pk_mul_f32 v[12:13], v[12:13], v[56:57] op_sel_hi:[1,0]
	v_pk_mul_f32 v[26:27], v[26:27], v[56:57] op_sel_hi:[1,0]
	v_pk_mul_f32 v[28:29], v[28:29], v[56:57] op_sel_hi:[1,0]
	v_pk_mul_f32 v[30:31], v[30:31], v[56:57] op_sel_hi:[1,0]
	v_pk_mul_f32 v[32:33], v[32:33], v[56:57] op_sel_hi:[1,0]
	v_pk_mul_f32 v[34:35], v[34:35], v[56:57] op_sel_hi:[1,0]
	v_pk_mul_f32 v[36:37], v[36:37], v[56:57] op_sel_hi:[1,0]
	s_waitcnt vmcnt(0)
	v_pk_mul_f32 v[6:7], v[92:93], v[6:7]
	v_pk_mul_f32 v[8:9], v[94:95], v[8:9]
	v_pk_add_f32 v[170:171], v[170:171], 1.0 op_sel_hi:[1,0]
	v_pk_add_f32 v[172:173], v[172:173], 1.0 op_sel_hi:[1,0]
	v_pk_fma_f32 v[6:7], v[170:171], v[6:7], v[202:203]
	v_pk_fma_f32 v[8:9], v[172:173], v[8:9], v[204:205]
	v_cvt_pk_bf16_f32 v92, v6, v7
	v_cvt_pk_bf16_f32 v93, v8, v9
	global_store_dwordx2 v[58:59], v[92:93], off
	v_pk_mul_f32 v[0:1], v[96:97], v[0:1]
	v_pk_mul_f32 v[2:3], v[98:99], v[2:3]
	v_pk_add_f32 v[174:175], v[174:175], 1.0 op_sel_hi:[1,0]
	v_pk_add_f32 v[176:177], v[176:177], 1.0 op_sel_hi:[1,0]
	v_pk_fma_f32 v[0:1], v[174:175], v[0:1], v[206:207]
	v_pk_fma_f32 v[2:3], v[176:177], v[2:3], v[208:209]
	v_cvt_pk_bf16_f32 v96, v0, v1
	v_cvt_pk_bf16_f32 v97, v2, v3
	global_store_dwordx2 v[58:59], v[96:97], off offset:512
	v_pk_mul_f32 v[22:23], v[100:101], v[22:23]
	v_pk_mul_f32 v[24:25], v[102:103], v[24:25]
	v_pk_add_f32 v[178:179], v[178:179], 1.0 op_sel_hi:[1,0]
	v_pk_add_f32 v[180:181], v[180:181], 1.0 op_sel_hi:[1,0]
	v_pk_fma_f32 v[22:23], v[178:179], v[22:23], v[210:211]
	v_pk_fma_f32 v[24:25], v[180:181], v[24:25], v[212:213]
	v_cvt_pk_bf16_f32 v100, v22, v23
	v_cvt_pk_bf16_f32 v101, v24, v25
	global_store_dwordx2 v[58:59], v[100:101], off offset:1024
	v_pk_mul_f32 v[18:19], v[104:105], v[18:19]
	v_pk_mul_f32 v[20:21], v[106:107], v[20:21]
	v_pk_add_f32 v[182:183], v[182:183], 1.0 op_sel_hi:[1,0]
	v_pk_add_f32 v[184:185], v[184:185], 1.0 op_sel_hi:[1,0]
	v_pk_fma_f32 v[18:19], v[182:183], v[18:19], v[214:215]
	v_pk_fma_f32 v[20:21], v[184:185], v[20:21], v[216:217]
	v_cvt_pk_bf16_f32 v104, v18, v19
	v_cvt_pk_bf16_f32 v105, v20, v21
	global_store_dwordx2 v[58:59], v[104:105], off offset:1536
	v_pk_mul_f32 v[10:11], v[108:109], v[10:11]
	v_pk_mul_f32 v[12:13], v[110:111], v[12:13]
	v_pk_add_f32 v[186:187], v[186:187], 1.0 op_sel_hi:[1,0]
	v_pk_add_f32 v[188:189], v[188:189], 1.0 op_sel_hi:[1,0]
	v_pk_fma_f32 v[10:11], v[186:187], v[10:11], v[218:219]
	v_pk_fma_f32 v[12:13], v[188:189], v[12:13], v[220:221]
	v_cvt_pk_bf16_f32 v108, v10, v11
	v_cvt_pk_bf16_f32 v109, v12, v13
	global_store_dwordx2 v[58:59], v[108:109], off offset:2048
	v_pk_mul_f32 v[26:27], v[112:113], v[26:27]
	v_pk_mul_f32 v[28:29], v[114:115], v[28:29]
	v_pk_add_f32 v[190:191], v[190:191], 1.0 op_sel_hi:[1,0]
	v_pk_add_f32 v[192:193], v[192:193], 1.0 op_sel_hi:[1,0]
	v_pk_fma_f32 v[26:27], v[190:191], v[26:27], v[222:223]
	v_pk_fma_f32 v[28:29], v[192:193], v[28:29], v[224:225]
	v_cvt_pk_bf16_f32 v112, v26, v27
	v_cvt_pk_bf16_f32 v113, v28, v29
	global_store_dwordx2 v[58:59], v[112:113], off offset:2560
	v_pk_mul_f32 v[30:31], v[116:117], v[30:31]
	v_pk_mul_f32 v[32:33], v[118:119], v[32:33]
	v_pk_add_f32 v[194:195], v[194:195], 1.0 op_sel_hi:[1,0]
	v_pk_add_f32 v[196:197], v[196:197], 1.0 op_sel_hi:[1,0]
	v_pk_fma_f32 v[30:31], v[194:195], v[30:31], v[226:227]
	v_pk_fma_f32 v[32:33], v[196:197], v[32:33], v[228:229]
	v_cvt_pk_bf16_f32 v116, v30, v31
	v_cvt_pk_bf16_f32 v117, v32, v33
	global_store_dwordx2 v[58:59], v[116:117], off offset:3072
	v_pk_mul_f32 v[34:35], v[120:121], v[34:35]
	v_pk_mul_f32 v[36:37], v[122:123], v[36:37]
	v_pk_add_f32 v[198:199], v[198:199], 1.0 op_sel_hi:[1,0]
	v_pk_add_f32 v[200:201], v[200:201], 1.0 op_sel_hi:[1,0]
	v_pk_fma_f32 v[34:35], v[198:199], v[34:35], v[230:231]
	v_pk_fma_f32 v[36:37], v[200:201], v[36:37], v[232:233]
	v_cvt_pk_bf16_f32 v120, v34, v35
	v_cvt_pk_bf16_f32 v121, v36, v37
	global_store_dwordx2 v[58:59], v[120:121], off offset:3584
	s_cbranch_scc1 .LBB0_453
.LBB0_449:
	s_cmpk_lt_i32 s4, 0x1000
	s_cselect_b64 s[64:65], -1, 0
	s_and_b64 s[18:19], s[64:65], exec
	s_cselect_b32 s19, s7, s61
	s_cselect_b32 s18, s6, s60
	s_cmpk_gt_i32 s4, 0x1fff
	v_lshl_add_u64 v[56:57], s[18:19], 0, v[52:53]
	s_cselect_b64 s[18:19], -1, 0
	s_and_b64 s[18:19], s[8:9], s[18:19]
	s_mov_b64 s[66:67], -1
	s_and_b64 vcc, exec, s[18:19]
	s_cbranch_vccnz .LBB0_451
	global_load_dwordx4 v[6:9], v[56:57], off
	global_load_dwordx4 v[0:3], v[56:57], off offset:1024
	global_load_dwordx4 v[22:25], v[56:57], off offset:2048
	global_load_dwordx4 v[18:21], v[56:57], off offset:3072
	v_add_co_u32_e32 v30, vcc, s90, v56
	s_mov_b64 s[66:67], 0
	s_nop 0
	v_addc_co_u32_e32 v31, vcc, 0, v57, vcc
	global_load_dwordx4 v[10:13], v[30:31], off
	global_load_dwordx4 v[26:29], v[30:31], off offset:1024
	global_load_dwordx4 v[34:37], v[30:31], off offset:3072
	s_nop 0
	global_load_dwordx4 v[30:33], v[30:31], off offset:2048
	s_add_i32 s3, s4, s10
	s_cmpk_gt_i32 s3, 0x2fff
	s_cbranch_scc1 .Lnpf_none
	s_cmpk_lt_i32 s3, 0x1000
	s_cselect_b32 s19, s7, s61
	s_cselect_b32 s18, s6, s60
	v_lshl_add_u64 v[124:125], v[52:53], 0, s[62:63]
	v_lshl_add_u64 v[124:125], s[18:19], 0, v[124:125]
	global_load_dwordx4 v[126:129], v[124:125], off
	global_load_dwordx4 v[126:129], v[124:125], off offset:1024
	global_load_dwordx4 v[126:129], v[124:125], off offset:2048
	global_load_dwordx4 v[126:129], v[124:125], off offset:3072
	v_add_co_u32_e32 v124, vcc, s90, v124
	s_nop 1
	v_addc_co_u32_e32 v125, vcc, 0, v125, vcc
	global_load_dwordx4 v[126:129], v[124:125], off
	global_load_dwordx4 v[126:129], v[124:125], off offset:1024
	global_load_dwordx4 v[126:129], v[124:125], off offset:2048
	global_load_dwordx4 v[126:129], v[124:125], off offset:3072
	s_waitcnt vmcnt(8)
	s_branch .Lnpf_go

.Lnpf_go:
	v_mov_b32_e32 v66, v7
	v_mov_b32_e32 v67, v1
	v_mov_b32_e32 v70, v9
	v_mov_b32_e32 v71, v3
	v_mov_b32_e32 v58, v6
	v_mov_b32_e32 v59, v0
	v_mov_b32_e32 v68, v8
	v_mov_b32_e32 v69, v2
	v_pk_mul_f32 v[72:73], v[24:25], v[24:25]
	v_pk_mul_f32 v[74:75], v[22:23], v[22:23]
	v_pk_mul_f32 v[66:67], v[66:67], v[66:67]
	v_pk_mul_f32 v[70:71], v[70:71], v[70:71]
	v_pk_mov_b32 v[80:81], v[74:75], v[72:73] op_sel:[1,0]
	v_mov_b32_e32 v75, v73
	v_pk_fma_f32 v[58:59], v[58:59], v[58:59], v[66:67]
	v_pk_fma_f32 v[66:67], v[68:69], v[68:69], v[70:71]
	v_mul_f32_e32 v76, v19, v19
	v_mul_f32_e32 v78, v21, v21
	v_pk_add_f32 v[68:69], v[80:81], v[74:75]
	v_pk_add_f32 v[58:59], v[58:59], v[66:67]
	v_mul_f32_e32 v55, v10, v10
	v_mul_f32_e32 v65, v11, v11
	v_mul_f32_e32 v85, v12, v12
	v_mul_f32_e32 v87, v13, v13
	v_pk_fma_f32 v[72:73], v[18:19], v[18:19], v[76:77] op_sel_hi:[1,1,0]
	v_pk_fma_f32 v[76:77], v[20:21], v[20:21], v[78:79] op_sel_hi:[1,1,0]
	v_pk_add_f32 v[66:67], v[68:69], v[68:69] op_sel:[0,1] op_sel_hi:[1,0]
	v_pk_add_f32 v[58:59], v[58:59], v[58:59] op_sel:[0,1] op_sel_hi:[1,0]
	v_pk_mul_f32 v[78:79], v[28:29], v[28:29]
	v_pk_mul_f32 v[82:83], v[26:27], v[26:27]
	v_mov_b32_e32 v73, v85
	v_mov_b32_e32 v77, v87
	v_mov_b32_e32 v67, v65
	v_mov_b32_e32 v59, v55
	v_pk_mov_b32 v[70:71], v[82:83], v[78:79] op_sel:[1,0]
	v_mov_b32_e32 v83, v79
	v_pk_add_f32 v[68:69], v[72:73], v[76:77]
	v_pk_add_f32 v[58:59], v[58:59], v[66:67]
	v_mul_f32_e32 v84, v31, v31
	v_mul_f32_e32 v86, v33, v33
	v_pk_add_f32 v[70:71], v[70:71], v[82:83]
	v_pk_add_f32 v[58:59], v[58:59], v[68:69]
	v_mul_f32_e32 v88, v34, v34
	v_mul_f32_e32 v89, v35, v35
	v_mul_f32_e32 v90, v36, v36
	v_mul_f32_e32 v91, v37, v37
	v_pk_fma_f32 v[74:75], v[30:31], v[30:31], v[84:85] op_sel_hi:[1,1,0]
	v_pk_fma_f32 v[78:79], v[32:33], v[32:33], v[86:87] op_sel_hi:[1,1,0]
	v_pk_add_f32 v[70:71], v[70:71], v[70:71] op_sel:[0,1] op_sel_hi:[1,0]
	v_pk_add_f32 v[58:59], v[58:59], v[58:59] op_sel:[0,1] op_sel_hi:[1,0]
	v_mov_b32_e32 v75, v90
	v_mov_b32_e32 v79, v91
	v_mov_b32_e32 v71, v89
	v_mov_b32_e32 v59, v88
	v_pk_add_f32 v[72:73], v[74:75], v[78:79]
	v_pk_add_f32 v[58:59], v[58:59], v[70:71]
	s_nop 0
	v_pk_add_f32 v[58:59], v[58:59], v[72:73]
	s_nop 0
	v_add_f32_e32 v55, v58, v59
